# P0: silu(cvec) staging loads and rope position loads issued up front instead of one load+wait per loop iteration
# speedup vs baseline: 1.0137x; 1.0064x over previous
.LBB0_20:
	s_mov_b64 s[6:7], 0x1000
	v_lshl_add_u64 v[8:9], v[0:1], 0, s[6:7]
	global_load_dword v16, v[8:9], off offset:-4096
	global_load_dword v17, v[8:9], off offset:-2048
	global_load_dword v18, v[8:9], off
	global_load_dword v19, v[8:9], off offset:2048
	s_mov_b64 s[6:7], 0x3000
	v_lshl_add_u64 v[10:11], v[0:1], 0, s[6:7]
	global_load_dword v20, v[10:11], off offset:-4096
	global_load_dword v21, v[10:11], off offset:-2048
	global_load_dword v22, v[10:11], off
	global_load_dword v23, v[10:11], off offset:2048
	s_mov_b64 s[6:7], 0x5000
	v_lshl_add_u64 v[12:13], v[0:1], 0, s[6:7]
	global_load_dword v24, v[12:13], off offset:-4096
	global_load_dword v25, v[12:13], off offset:-2048
	global_load_dword v26, v[12:13], off
	global_load_dword v27, v[12:13], off offset:2048
	s_mov_b64 s[6:7], 0x7000
	v_lshl_add_u64 v[14:15], v[0:1], 0, s[6:7]
	global_load_dword v28, v[14:15], off offset:-4096
	global_load_dword v29, v[14:15], off offset:-2048
	global_load_dword v30, v[14:15], off
	global_load_dword v31, v[14:15], off offset:2048
	s_waitcnt vmcnt(0)
	v_mul_f32_e32 v32, 0xbfb8aa3b, v16
	v_mul_f32_e32 v33, 0xbfb8aa3b, v17
	v_mul_f32_e32 v34, 0xbfb8aa3b, v18
	v_mul_f32_e32 v35, 0xbfb8aa3b, v19
	v_mul_f32_e32 v36, 0xbfb8aa3b, v20
	v_mul_f32_e32 v37, 0xbfb8aa3b, v21
	v_mul_f32_e32 v38, 0xbfb8aa3b, v22
	v_mul_f32_e32 v39, 0xbfb8aa3b, v23
	v_mul_f32_e32 v40, 0xbfb8aa3b, v24
	v_mul_f32_e32 v41, 0xbfb8aa3b, v25
	v_mul_f32_e32 v42, 0xbfb8aa3b, v26
	v_mul_f32_e32 v43, 0xbfb8aa3b, v27
	v_mul_f32_e32 v44, 0xbfb8aa3b, v28
	v_mul_f32_e32 v45, 0xbfb8aa3b, v29
	v_mul_f32_e32 v46, 0xbfb8aa3b, v30
	v_mul_f32_e32 v47, 0xbfb8aa3b, v31
	v_exp_f32_e32 v32, v32
	v_exp_f32_e32 v33, v33
	v_exp_f32_e32 v34, v34
	v_exp_f32_e32 v35, v35
	v_exp_f32_e32 v36, v36
	v_exp_f32_e32 v37, v37
	v_exp_f32_e32 v38, v38
	v_exp_f32_e32 v39, v39
	v_exp_f32_e32 v40, v40
	v_exp_f32_e32 v41, v41
	v_exp_f32_e32 v42, v42
	v_exp_f32_e32 v43, v43
	v_exp_f32_e32 v44, v44
	v_exp_f32_e32 v45, v45
	v_exp_f32_e32 v46, v46
	v_exp_f32_e32 v47, v47
	s_nop 0
	v_add_f32_e32 v32, 1.0, v32
	v_add_f32_e32 v33, 1.0, v33
	v_add_f32_e32 v34, 1.0, v34
	v_add_f32_e32 v35, 1.0, v35
	v_add_f32_e32 v36, 1.0, v36
	v_add_f32_e32 v37, 1.0, v37
	v_add_f32_e32 v38, 1.0, v38
	v_add_f32_e32 v39, 1.0, v39
	v_add_f32_e32 v40, 1.0, v40
	v_add_f32_e32 v41, 1.0, v41
	v_add_f32_e32 v42, 1.0, v42
	v_add_f32_e32 v43, 1.0, v43
	v_add_f32_e32 v44, 1.0, v44
	v_add_f32_e32 v45, 1.0, v45
	v_add_f32_e32 v46, 1.0, v46
	v_add_f32_e32 v47, 1.0, v47
	v_rcp_f32_e32 v32, v32
	v_rcp_f32_e32 v33, v33
	v_rcp_f32_e32 v34, v34
	v_rcp_f32_e32 v35, v35
	v_rcp_f32_e32 v36, v36
	v_rcp_f32_e32 v37, v37
	v_rcp_f32_e32 v38, v38
	v_rcp_f32_e32 v39, v39
	v_rcp_f32_e32 v40, v40
	v_rcp_f32_e32 v41, v41
	v_rcp_f32_e32 v42, v42
	v_rcp_f32_e32 v43, v43
	v_rcp_f32_e32 v44, v44
	v_rcp_f32_e32 v45, v45
	v_rcp_f32_e32 v46, v46
	v_rcp_f32_e32 v47, v47
	s_nop 0
	v_mul_f32_e32 v16, v16, v32
	v_mul_f32_e32 v17, v17, v33
	v_mul_f32_e32 v18, v18, v34
	v_mul_f32_e32 v19, v19, v35
	v_mul_f32_e32 v20, v20, v36
	v_mul_f32_e32 v21, v21, v37
	v_mul_f32_e32 v22, v22, v38
	v_mul_f32_e32 v23, v23, v39
	v_mul_f32_e32 v24, v24, v40
	v_mul_f32_e32 v25, v25, v41
	v_mul_f32_e32 v26, v26, v42
	v_mul_f32_e32 v27, v27, v43
	v_mul_f32_e32 v28, v28, v44
	v_mul_f32_e32 v29, v29, v45
	v_mul_f32_e32 v30, v30, v46
	v_mul_f32_e32 v31, v31, v47
	ds_write_b32 v3, v16
	ds_write_b32 v3, v17 offset:2048
	ds_write_b32 v3, v18 offset:4096
	ds_write_b32 v3, v19 offset:6144
	ds_write_b32 v3, v20 offset:8192
	ds_write_b32 v3, v21 offset:10240
	ds_write_b32 v3, v22 offset:12288
	ds_write_b32 v3, v23 offset:14336
	ds_write_b32 v3, v24 offset:16384
	ds_write_b32 v3, v25 offset:18432
	ds_write_b32 v3, v26 offset:20480
	ds_write_b32 v3, v27 offset:22528
	ds_write_b32 v3, v28 offset:24576
	ds_write_b32 v3, v29 offset:26624
	ds_write_b32 v3, v30 offset:28672
	ds_write_b32 v3, v31 offset:30720

.LBB0_28:
	s_or_b64 exec, exec, s[2:3]
	s_lshl_b32 s2, s90, 9
	v_writelane_b32 v254, s2, 25
	s_nop 1
	v_writelane_b32 v254, s3, 26
	s_mov_b32 s2, 0x80000
	v_cmp_gt_i32_e32 vcc, s2, v0
	s_and_saveexec_b64 s[2:3], vcc
	s_cbranch_execz .LBB0_35
	v_and_b32_e32 v1, 15, v141
	v_cvt_f32_ubyte0_e32 v1, v1
	v_mul_f32_e32 v1, 0xbd800000, v1
	v_mov_b32_e32 v2, 0x461c4000
	v_cmp_eq_f32_e32 vcc, 0, v1
	s_mov_b32 s4, 0x3f2aaaab
	s_movk_i32 s6, 0x204
	v_cndmask_b32_e64 v12, v2, 1.0, vcc
	v_frexp_mant_f32_e32 v2, v12
	v_cmp_gt_f32_e64 s[4:5], s4, v2
	s_mov_b32 s8, 0x42b17218
	s_mov_b32 s7, 0x7f800000
	v_cndmask_b32_e64 v3, 1.0, 2.0, s[4:5]
	v_mul_f32_e32 v2, v2, v3
	v_add_f32_e32 v5, 1.0, v2
	v_rcp_f32_e32 v10, v5
	v_add_f32_e32 v3, -1.0, v5
	v_sub_f32_e32 v7, v2, v3
	v_add_f32_e32 v3, -1.0, v2
	v_mul_f32_e32 v11, v3, v10
	v_mul_f32_e32 v4, v5, v11
	v_fma_f32 v6, v11, v5, -v4
	v_fmac_f32_e32 v6, v11, v7
	v_add_f32_e32 v2, v4, v6
	v_sub_f32_e32 v5, v3, v2
	v_pk_add_f32 v[8:9], v[2:3], v[4:5] neg_lo:[0,1] neg_hi:[0,1]
	v_mov_b32_e32 v7, v2
	v_pk_add_f32 v[2:3], v[8:9], v[6:7] neg_lo:[0,1] neg_hi:[0,1]
	v_mov_b32_e32 v6, 0x3e91f4c4
	v_add_f32_e32 v2, v2, v3
	v_add_f32_e32 v2, v5, v2
	v_mul_f32_e32 v3, v10, v2
	v_add_f32_e32 v2, v11, v3
	v_sub_f32_e32 v4, v2, v11
	v_sub_f32_e32 v13, v3, v4
	v_mul_f32_e32 v3, v2, v2
	v_fma_f32 v5, v2, v2, -v3
	v_add_f32_e32 v4, v13, v13
	v_fmac_f32_e32 v5, v2, v4
	v_add_f32_e32 v4, v3, v5
	v_fmac_f32_e32 v6, 0x3e76c4e1, v4
	v_fmaak_f32 v6, v4, v6, 0x3ecccdef
	v_sub_f32_e32 v3, v4, v3
	v_sub_f32_e32 v14, v5, v3
	v_mul_f32_e32 v3, v4, v6
	v_fma_f32 v5, v4, v6, -v3
	v_fmac_f32_e32 v5, v14, v6
	v_add_f32_e32 v6, v3, v5
	v_add_f32_e32 v7, 0x3f2aaaaa, v6
	v_sub_f32_e32 v3, v6, v3
	v_sub_f32_e32 v3, v5, v3
	v_add_f32_e32 v5, 0xbf2aaaaa, v7
	v_add_f32_e32 v3, 0x31739010, v3
	v_sub_f32_e32 v5, v6, v5
	v_pk_mul_f32 v[8:9], v[2:3], v[4:5]
	v_pk_add_f32 v[10:11], v[2:3], v[4:5]
	v_fma_f32 v6, v4, v2, -v8
	v_fmac_f32_e32 v6, v4, v13
	v_mov_b32_e32 v9, v11
	v_fmac_f32_e32 v6, v14, v2
	v_pk_add_f32 v[4:5], v[8:9], v[6:7]
	v_ldexp_f32 v14, v13, 1
	v_sub_f32_e32 v3, v4, v8
	v_sub_f32_e32 v3, v6, v3
	v_sub_f32_e32 v6, v7, v5
	v_add_f32_e32 v9, v11, v6
	v_pk_mul_f32 v[6:7], v[4:5], v[4:5] op_sel:[0,1] op_sel_hi:[1,0]
	v_cvt_f64_f32_e32 v[10:11], v12
	v_frexp_exp_i32_f64_e32 v7, v[10:11]
	v_subbrev_co_u32_e64 v7, s[4:5], 0, v7, s[4:5]
	v_cvt_f32_i32_e32 v7, v7
	v_fma_f32 v8, v4, v5, -v6
	v_fmac_f32_e32 v8, v4, v9
	s_mov_b32 s4, 0x3f317218
	v_mul_f32_e32 v4, 0x3f317218, v7
	v_fmac_f32_e32 v8, v3, v5
	v_fma_f32 v3, v7, s4, -v4
	v_fmamk_f32 v10, v7, 0xb102e308, v3
	v_ldexp_f32 v11, v2, 1
	v_add_f32_e32 v5, v6, v8
	v_pk_add_f32 v[2:3], v[4:5], v[10:11]
	v_mov_b32_e32 v12, v5
	v_mov_b32_e32 v13, v3
	v_mov_b32_e32 v7, v11
	v_pk_add_f32 v[6:7], v[12:13], v[6:7] neg_lo:[0,1] neg_hi:[0,1]
	v_mov_b32_e32 v9, v5
	v_pk_add_f32 v[6:7], v[8:9], v[6:7] neg_lo:[0,1] neg_hi:[0,1]
	v_mov_b32_e32 v11, v2
	v_add_f32_e32 v5, v14, v6
	v_add_f32_e32 v5, v5, v7
	v_pk_add_f32 v[6:7], v[2:3], v[4:5] neg_lo:[0,1] neg_hi:[0,1]
	v_pk_add_f32 v[8:9], v[2:3], v[4:5]
	v_mov_b32_e32 v4, v5
	v_mov_b32_e32 v7, v9
	v_pk_add_f32 v[12:13], v[10:11], v[6:7] neg_lo:[0,1] neg_hi:[0,1]
	v_pk_add_f32 v[6:7], v[10:11], v[6:7]
	v_mov_b32_e32 v5, v2
	v_pk_add_f32 v[10:11], v[6:7], v[2:3] op_sel:[1,0] op_sel_hi:[0,1] neg_lo:[0,1] neg_hi:[0,1]
	v_pk_add_f32 v[14:15], v[8:9], v[10:11] op_sel_hi:[1,0] neg_lo:[0,1] neg_hi:[0,1]
	v_mov_b32_e32 v8, v9
	v_mov_b32_e32 v9, v7
	v_pk_mov_b32 v[10:11], v[2:3], v[10:11] op_sel:[1,0]
	v_mov_b32_e32 v14, v12
	v_pk_add_f32 v[8:9], v[8:9], v[10:11] neg_lo:[0,1] neg_hi:[0,1]
	v_mov_b32_e32 v13, v7
	v_pk_add_f32 v[2:3], v[4:5], v[8:9] neg_lo:[0,1] neg_hi:[0,1]
	s_mov_b64 s[12:13], 0
	v_pk_add_f32 v[4:5], v[14:15], v[2:3]
	s_brev_b32 s16, 18
	v_pk_add_f32 v[8:9], v[4:5], v[4:5] op_sel:[0,1] op_sel_hi:[1,0]
	s_mov_b32 s17, 0xfe5163ab
	v_pk_add_f32 v[6:7], v[6:7], v[8:9] op_sel:[1,0] op_sel_hi:[0,1]
	v_mov_b32_e32 v5, v6
	v_pk_add_f32 v[10:11], v[4:5], v[12:13] neg_lo:[0,1] neg_hi:[0,1]
	v_mov_b32_e32 v3, v8
	v_sub_f32_e32 v4, v4, v10
	v_pk_add_f32 v[2:3], v[2:3], v[10:11] neg_lo:[0,1] neg_hi:[0,1]
	v_sub_f32_e32 v4, v12, v4
	v_add_f32_e32 v2, v2, v4
	v_add_f32_e32 v2, v2, v3
	v_add_f32_e32 v3, v6, v2
	v_sub_f32_e32 v4, v3, v6
	v_sub_f32_e32 v2, v2, v4
	v_mul_f32_e32 v4, v1, v3
	v_fma_f32 v3, v1, v3, -v4
	v_fmac_f32_e32 v3, v1, v2
	v_add_f32_e32 v2, v4, v3
	v_cmp_class_f32_e64 s[4:5], v4, s6
	v_sub_f32_e32 v5, v2, v4
	v_sub_f32_e32 v3, v3, v5
	v_cndmask_b32_e64 v2, v2, v4, s[4:5]
	v_mov_b32_e32 v4, 0x37000000
	v_cmp_eq_f32_e64 s[4:5], s8, v2
	s_mov_b32 s18, 0x3c439041
	s_mov_b32 s19, 0xdb629599
	v_cndmask_b32_e64 v4, 0, v4, s[4:5]
	v_sub_f32_e32 v5, v2, v4
	s_mov_b32 s4, 0x3fb8aa3b
	v_mul_f32_e32 v6, 0x3fb8aa3b, v5
	v_fma_f32 v7, v5, s4, -v6
	v_rndne_f32_e32 v8, v6
	v_fmamk_f32 v7, v5, 0x32a5705f, v7
	v_sub_f32_e32 v6, v6, v8
	v_add_f32_e32 v6, v6, v7
	v_exp_f32_e32 v6, v6
	v_cvt_i32_f32_e32 v7, v8
	v_cmp_neq_f32_e64 s[4:5], |v2|, s7
	s_mov_b32 s20, 0xf534ddc0
	s_mov_b32 s21, 0xfc2757d1
	v_cndmask_b32_e64 v2, 0, v3, s[4:5]
	s_mov_b32 s4, 0xc2ce8ed0
	v_ldexp_f32 v3, v6, v7
	v_cmp_ngt_f32_e64 s[4:5], s4, v5
	v_add_f32_e32 v2, v4, v2
	v_mov_b32_e32 v4, 0x7f800000
	v_cndmask_b32_e64 v3, 0, v3, s[4:5]
	v_cmp_nlt_f32_e64 s[4:5], s8, v5
	v_mov_b32_e32 v5, 0
	s_mov_b32 s22, 0x4e441529
	v_cndmask_b32_e64 v3, v4, v3, s[4:5]
	v_fma_f32 v2, v3, v2, v3
	v_cmp_class_f32_e64 s[4:5], v3, s6
	s_mov_b32 s23, 0xa2f9836e
	s_mov_b32 s24, 0x3fc90fda
	v_cndmask_b32_e64 v2, v2, v3, s[4:5]
	v_cmp_neq_f32_e64 s[4:5], v1, |v1|
	s_mov_b32 s25, 0x3f22f983
	s_mov_b32 s26, 0xbfc90fda
	v_cndmask_b32_e64 v3, v4, 0, s[4:5]
	v_cndmask_b32_e64 v3, v3, 1.0, vcc
	v_cmp_class_f32_e64 s[4:5], v1, s6
	v_mov_b32_e32 v6, 0x3c0881c4
	v_mov_b32_e32 v7, 0xbab64f3b
	v_cndmask_b32_e64 v1, |v2|, v3, s[4:5]
	v_readlane_b32 s4, v254, 20
	v_readlane_b32 s5, v254, 19
	s_add_i32 s4, s4, s5
	v_add_u32_e32 v2, s4, v140
	v_ashrrev_i32_e32 v3, 31, v2
	v_lshl_add_u64 v[2:3], v[2:3], 2, s[82:83]
	s_mov_b64 s[4:5], 0x300000
	v_lshl_add_u64 v[2:3], v[2:3], 0, s[4:5]
	v_readlane_b32 s4, v254, 25
	v_readlane_b32 s5, v254, 26
	s_mov_b32 s6, s4
	s_ashr_i32 s7, s4, 31
	v_writelane_b32 v254, s4, 25
	s_lshl_b64 s[10:11], s[6:7], 2
	s_brev_b32 s27, 1
	v_writelane_b32 v254, s5, 26
	s_movk_i32 s28, 0x1f8
	s_mov_b32 s29, 0x7ffff
	v_not_b32_e32 v8, 63
	v_not_b32_e32 v9, 31
	v_mov_b32_e32 v10, 0x7fc00000
	s_load_dwordx16 s[36:51], s[0:1], 0x0
	v_ashrrev_i32_e32 v30, 4, v0
	v_ashrrev_i32_e32 v31, 31, v30
	s_waitcnt lgkmcnt(0)
	v_lshl_add_u64 v[30:31], v[30:31], 2, s[40:41]
	global_load_dword v34, v[30:31], off
	v_add_co_u32_e32 v32, vcc, 0x8000, v30
	s_nop 1
	v_addc_co_u32_e32 v33, vcc, 0, v31, vcc
	global_load_dword v35, v[32:33], off
	v_add_co_u32_e32 v32, vcc, 0x10000, v30
	s_nop 1
	v_addc_co_u32_e32 v33, vcc, 0, v31, vcc
	global_load_dword v36, v[32:33], off
	v_add_co_u32_e32 v32, vcc, 0x18000, v30
	s_nop 1
	v_addc_co_u32_e32 v33, vcc, 0, v31, vcc
	global_load_dword v37, v[32:33], off
	s_waitcnt vmcnt(0)
	s_branch .LBB0_31

.LBB0_31:
	v_mov_b32_e32 v4, v34
	v_mov_b32_e32 v34, v35
	v_mov_b32_e32 v35, v36
	v_mov_b32_e32 v36, v37
	v_cvt_f32_i32_e32 v4, v4
	v_mul_f32_e32 v11, v1, v4
	v_and_b32_e32 v12, 0x7fffffff, v11
	v_cmp_nlt_f32_e64 s[4:5], |v11|, s16
	s_and_saveexec_b64 s[6:7], s[4:5]
	s_xor_b64 s[14:15], exec, s[6:7]
	s_cbranch_execz .LBB0_33
	v_lshrrev_b32_e32 v4, 23, v12
	v_add_u32_e32 v4, 0xffffff88, v4
	v_cmp_lt_u32_e32 vcc, 63, v4
	s_nop 1
	v_cndmask_b32_e32 v13, 0, v8, vcc
	v_add_u32_e32 v4, v13, v4
	v_cmp_lt_u32_e64 s[4:5], 31, v4
	s_nop 1
	v_cndmask_b32_e64 v13, 0, v9, s[4:5]
	v_add_u32_e32 v4, v13, v4
	v_cmp_lt_u32_e64 s[6:7], 31, v4
	s_nop 1
	v_cndmask_b32_e64 v13, 0, v9, s[6:7]
	v_add_u32_e32 v13, v13, v4
	v_and_b32_e32 v4, 0x7fffff, v12
	v_or_b32_e32 v26, 0x800000, v4
	v_mad_u64_u32 v[14:15], s[8:9], v26, s17, 0
	v_mov_b32_e32 v4, v15
	v_mad_u64_u32 v[16:17], s[8:9], v26, s18, v[4:5]
	v_mov_b32_e32 v4, v17
	v_mad_u64_u32 v[18:19], s[8:9], v26, s19, v[4:5]
	v_mov_b32_e32 v4, v19
	v_mad_u64_u32 v[20:21], s[8:9], v26, s20, v[4:5]
	v_mov_b32_e32 v4, v21
	v_mad_u64_u32 v[22:23], s[8:9], v26, s21, v[4:5]
	v_mov_b32_e32 v4, v23
	v_mad_u64_u32 v[24:25], s[8:9], v26, s22, v[4:5]
	v_mov_b32_e32 v4, v25
	v_mad_u64_u32 v[26:27], s[8:9], v26, s23, v[4:5]
	v_cndmask_b32_e32 v15, v24, v20, vcc
	v_cndmask_b32_e32 v4, v26, v22, vcc
	v_cndmask_b32_e32 v19, v27, v24, vcc
	v_cndmask_b32_e64 v17, v4, v15, s[4:5]
	v_cndmask_b32_e64 v4, v19, v4, s[4:5]
	v_cndmask_b32_e32 v19, v22, v18, vcc
	v_cndmask_b32_e64 v15, v15, v19, s[4:5]
	v_cndmask_b32_e64 v4, v4, v17, s[6:7]
	v_cndmask_b32_e64 v17, v17, v15, s[6:7]
	v_sub_u32_e32 v21, 32, v13
	v_alignbit_b32 v22, v4, v17, v21
	v_cmp_eq_u32_e64 s[8:9], 0, v13
	v_cndmask_b32_e32 v14, v18, v14, vcc
	s_nop 0
	v_cndmask_b32_e64 v13, v22, v4, s[8:9]
	v_cndmask_b32_e32 v4, v20, v16, vcc
	v_cndmask_b32_e64 v16, v19, v4, s[4:5]
	v_cndmask_b32_e64 v15, v15, v16, s[6:7]
	v_alignbit_b32 v19, v17, v15, v21
	v_cndmask_b32_e64 v17, v19, v17, s[8:9]
	v_bfe_u32 v22, v13, 29, 1
	v_cndmask_b32_e64 v4, v4, v14, s[4:5]
	v_alignbit_b32 v19, v13, v17, 30
	v_sub_u32_e32 v23, 0, v22
	v_cndmask_b32_e64 v4, v16, v4, s[6:7]
	v_xor_b32_e32 v19, v19, v23
	v_alignbit_b32 v14, v15, v4, v21
	v_cndmask_b32_e64 v14, v14, v15, s[8:9]
	v_ffbh_u32_e32 v16, v19
	v_alignbit_b32 v15, v17, v14, 30
	v_min_u32_e32 v16, 32, v16
	v_alignbit_b32 v4, v14, v4, 30
	v_xor_b32_e32 v15, v15, v23
	v_sub_u32_e32 v17, 31, v16
	v_xor_b32_e32 v4, v4, v23
	v_alignbit_b32 v18, v19, v15, v17
	v_alignbit_b32 v4, v15, v4, v17
	v_alignbit_b32 v14, v18, v4, 9
	v_ffbh_u32_e32 v15, v14
	v_min_u32_e32 v15, 32, v15
	v_lshrrev_b32_e32 v20, 29, v13
	v_not_b32_e32 v17, v15
	v_alignbit_b32 v4, v14, v4, v17
	v_lshlrev_b32_e32 v14, 31, v20
	v_or_b32_e32 v17, 0x33000000, v14
	v_add_lshl_u32 v15, v15, v16, 23
	v_lshrrev_b32_e32 v4, 9, v4
	v_sub_u32_e32 v15, v17, v15
	v_or_b32_e32 v14, 0.5, v14
	v_lshlrev_b32_e32 v16, 23, v16
	v_or_b32_e32 v4, v15, v4
	v_lshrrev_b32_e32 v15, 9, v18
	v_sub_u32_e32 v14, v14, v16
	v_or_b32_e32 v14, v15, v14
	v_mul_f32_e32 v15, 0x3fc90fda, v14
	v_fma_f32 v16, v14, s24, -v15
	v_fmac_f32_e32 v16, 0x33a22168, v14
	v_fmac_f32_e32 v16, 0x3fc90fda, v4
	v_lshrrev_b32_e32 v13, 30, v13
	v_add_f32_e32 v4, v15, v16
	v_add_u32_e32 v13, v22, v13
